# P2x scan loop: raw-row conversions moved one more sub-chunk later (each parity converted at the end of the other parity's sub-chunk, vmcnt(13) keeps the newest loads in flight)
# speedup vs baseline: 1.0936x; 1.0028x over previous
.LBB0_554:
	s_waitcnt vmcnt(1)
	v_lshlrev_b32_e32 v0, 16, v75
	v_readlane_b32 s0, v248, 2
	v_cndmask_b32_e64 v0, 0, v0, s[8:9]
	v_add_u32_e32 v137, s78, v162
	v_lshlrev_b32_e32 v1, 16, v81
	v_add_u32_e32 v139, s0, v162
	s_add_i32 s0, s70, s41
	s_mul_i32 s40, s40, 7
	ds_write_b32 v137, v0 offset:13824
	v_add_f32_e32 v0, 0, v0
	v_cndmask_b32_e64 v1, 0, v1, s[8:9]
	s_sub_i32 s0, s0, s40
	v_add_f32_e32 v0, v0, v1
	s_lshl_b32 s0, s0, 8
	ds_write_b32 v139, v1 offset:13824
	ds_write_b32 v163, v0 offset:22016
	s_add_i32 s72, s48, s0
	v_mov_b32_e32 v12, v91
	v_mov_b32_e32 v13, v109
	v_mov_b32_e32 v14, v111
	v_mov_b32_e32 v15, v113
	v_mov_b32_e32 v8, v115
	v_mov_b32_e32 v9, v117
	v_mov_b32_e32 v10, v119
	v_mov_b32_e32 v11, v122
	v_mov_b32_e32 v4, v123
	v_mov_b32_e32 v5, v124
	v_mov_b32_e32 v6, v125
	v_mov_b32_e32 v7, v126
	v_mov_b32_e32 v0, v127
	v_mov_b32_e32 v1, v129
	v_mov_b32_e32 v2, v130
	v_mov_b32_e32 v3, v131
	s_waitcnt vmcnt(0)
	s_branch .LBB0_556

.LBB0_556:
	s_waitcnt lgkmcnt(0)
	s_barrier
	ds_read2st64_b32 v[184:185], v162 offset0:86 offset1:87
	ds_read2st64_b32 v[186:187], v162 offset0:88 offset1:89
	ds_read2st64_b32 v[188:189], v162 offset0:90 offset1:91
	ds_read_b32 v190, v162 offset:23552
	s_waitcnt lgkmcnt(0)
	s_and_b64 vcc, exec, s[38:39]
	v_add_f32_e32 v16, 0, v184
	v_cndmask_b32_e64 v16, v16, 0, s[4:5]
	v_cndmask_b32_e64 v17, 0, v185, s[10:11]
	v_add_f32_e32 v18, v16, v17
	v_cndmask_b32_e64 v16, 0, v186, s[12:13]
	v_add_f32_e32 v16, v18, v16
	v_cndmask_b32_e64 v17, 0, v187, s[14:15]
	v_add_f32_e32 v18, v16, v17
	v_cndmask_b32_e64 v16, 0, v188, s[16:17]
	v_add_f32_e32 v16, v18, v16
	v_cndmask_b32_e64 v17, 0, v189, s[18:19]
	v_add_f32_e32 v16, v16, v17
	v_cndmask_b32_e64 v17, 0, v190, s[20:21]
	v_add_f32_e32 v16, v16, v17
	v_mov_b32_e32 v17, 0
	s_cbranch_vccnz .LBB0_558
	v_and_b32_e32 v25, 0xffff0000, v77
	v_lshlrev_b32_e32 v24, 16, v77
	v_pk_add_f32 v[28:29], v[94:95], v[24:25] neg_lo:[0,1] neg_hi:[0,1]
	v_mov_b32_e32 v27, v25
	v_fmac_f32_e32 v27, v63, v29
	v_mov_b32_e32 v30, v24
	v_mul_f32_e32 v20, v65, v27
	s_waitcnt vmcnt(13)
	v_fmac_f32_e32 v30, v69, v28
	v_mul_f32_e32 v28, v20, v20
	ds_read_b32 v19, v137 offset:13824
	v_mul_f32_e32 v18, 0xbfb8aa3b, v16
	v_mov_b32_dpp v28, v28 quad_perm:[1,0,3,2] row_mask:0xf bank_mask:0xf bound_ctrl:1
	v_fmac_f32_e32 v28, v20, v20
	v_exp_f32_e32 v18, v18
	s_waitcnt lgkmcnt(0)
	v_add_f32_e32 v16, v16, v19
	v_add_f32_dpp v28, v28, v28 quad_perm:[2,3,0,1] row_mask:0xf bank_mask:0xf bound_ctrl:1
	v_mul_f32_e32 v19, 0xbfb8aa3b, v16
	v_exp_f32_e32 v21, v19
	v_add_f32_dpp v28, v28, v28 row_ror:4 row_mask:0xf bank_mask:0xf bound_ctrl:1
	v_mul_f32_e32 v19, 0x3fb8aa3b, v16
	v_lshlrev_b32_e32 v23, 16, v73
	v_add_f32_dpp v28, v28, v28 row_ror:8 row_mask:0xf bank_mask:0xf bound_ctrl:1
	v_exp_f32_e32 v22, v19
	v_readlane_b32 s3, v28, 16
	v_readlane_b32 s40, v28, 48
	v_readlane_b32 s0, v28, 0
	v_readlane_b32 s1, v28, 32
	v_mov_b32_e32 v28, s3
	v_mov_b32_e32 v29, s40
	v_pk_add_f32 v[28:29], s[0:1], v[28:29]
	v_sub_f32_e32 v19, v135, v23
	v_add_f32_e32 v28, v28, v29
	v_fma_f32 v19, v61, v19, v23
	v_rsq_f32_e32 v28, v28
	v_lshlrev_b32_e32 v26, 16, v79
	v_mov_b32_e32 v135, v23
	v_mov_b64_e32 v[94:95], v[24:25]
	v_min_f32_e32 v28, 0x5368d4a5, v28
	s_nop 0
	v_mul_f32_e32 v28, v20, v28
	v_xor_b32_e32 v20, 0x80000000, v28
	v_pk_mul_f32 v[18:19], v[18:19], v[20:21]
	s_nop 0
	v_cvt_pk_bf16_f32 v18, v18, v19
	v_add_f32_e32 v19, -1.0, v26
	v_fma_f32 v29, v67, v19, 1.0
	v_pk_mul_f32 v[20:21], v[28:29], v[26:27]
	s_nop 0
	v_pk_mul_f32 v[20:21], v[22:23], v[20:21] op_sel_hi:[0,1]
	v_bfe_u32 v22, v30, 16, 1
	v_cvt_pk_bf16_f32 v19, v20, v21
	v_add3_u32 v22, v30, v22, s51
	v_lshrrev_b32_e32 v20, 16, v18
	v_lshrrev_b32_e32 v21, 16, v19
	v_lshrrev_b32_e32 v22, 16, v22
	s_branch .LBB0_559

.LBB0_559:
	s_and_b64 vcc, exec, s[38:39]
	ds_write_b16 v167, v18
	ds_write_b16 v167, v20 offset:2304
	ds_write_b16 v167, v19 offset:4608
	ds_write_b16 v167, v21 offset:6912
	ds_write_b16 v167, v22 offset:9216
	s_cbranch_vccnz .LBB0_561
	v_mul_f32_e32 v17, 0xbfb8aa3b, v16
	v_exp_f32_e32 v18, v17
	ds_read_b32 v17, v139 offset:13824
	v_and_b32_e32 v25, 0xffff0000, v83
	v_lshlrev_b32_e32 v24, 16, v83
	v_lshlrev_b32_e32 v23, 16, v71
	v_pk_add_f32 v[28:29], v[94:95], v[24:25] neg_lo:[0,1] neg_hi:[0,1]
	s_waitcnt lgkmcnt(0)
	v_add_f32_e32 v16, v16, v17
	v_mul_f32_e32 v17, 0xbfb8aa3b, v16
	v_exp_f32_e32 v21, v17
	v_mul_f32_e32 v17, 0x3fb8aa3b, v16
	v_mov_b32_e32 v27, v25
	v_exp_f32_e32 v22, v17
	v_sub_f32_e32 v17, v135, v23
	v_fmac_f32_e32 v27, v63, v29
	v_fma_f32 v19, v61, v17, v23
	v_mul_f32_e32 v17, v65, v27
	v_mul_f32_e32 v20, v17, v17
	v_mov_b32_e32 v30, v24
	s_waitcnt vmcnt(13)
	v_fmac_f32_e32 v30, v69, v28
	v_mov_b32_dpp v20, v20 quad_perm:[1,0,3,2] row_mask:0xf bank_mask:0xf bound_ctrl:1
	v_fmac_f32_e32 v20, v17, v17
	v_lshlrev_b32_e32 v26, 16, v85
	v_mov_b32_e32 v135, v23
	v_add_f32_dpp v20, v20, v20 quad_perm:[2,3,0,1] row_mask:0xf bank_mask:0xf bound_ctrl:1
	v_mov_b64_e32 v[94:95], v[24:25]
	s_nop 0
	v_add_f32_dpp v20, v20, v20 row_ror:4 row_mask:0xf bank_mask:0xf bound_ctrl:1
	s_nop 1
	v_add_f32_dpp v20, v20, v20 row_ror:8 row_mask:0xf bank_mask:0xf bound_ctrl:1
	s_nop 0
	v_readlane_b32 s3, v20, 16
	v_readlane_b32 s40, v20, 48
	v_readlane_b32 s0, v20, 0
	v_readlane_b32 s1, v20, 32
	v_mov_b32_e32 v28, s3
	v_mov_b32_e32 v29, s40
	v_pk_add_f32 v[28:29], s[0:1], v[28:29]
	s_nop 0
	v_add_f32_e32 v20, v28, v29
	v_rsq_f32_e32 v20, v20
	s_nop 0
	v_min_f32_e32 v20, 0x5368d4a5, v20
	s_nop 0
	v_mul_f32_e32 v28, v17, v20
	v_xor_b32_e32 v20, 0x80000000, v28
	v_pk_mul_f32 v[18:19], v[18:19], v[20:21]
	v_bfe_u32 v21, v30, 16, 1
	v_cvt_pk_bf16_f32 v17, v18, v19
	v_add_f32_e32 v18, -1.0, v26
	v_fma_f32 v29, v67, v18, 1.0
	v_pk_mul_f32 v[18:19], v[28:29], v[26:27]
	v_add3_u32 v21, v30, v21, s51
	v_pk_mul_f32 v[18:19], v[22:23], v[18:19] op_sel_hi:[0,1]
	v_cvt_pk_bf16_f32 v18, v18, v19
	v_lshrrev_b32_e32 v19, 16, v17
	v_lshrrev_b32_e32 v20, 16, v18
	v_lshrrev_b32_e32 v21, 16, v21
	s_branch .LBB0_562

.LBB0_584:
	s_cmp_lt_u32 s2, 14
	s_cbranch_scc1 .Lx584_w
	s_waitcnt vmcnt(0)
.Lx584_w:
	s_waitcnt vmcnt(13)
	s_cmp_eq_u32 s2, 0
	s_cbranch_scc1 .Lx584_c
	v_lshlrev_b32_e32 v142, 16, v198
	v_lshlrev_b32_e32 v97, 16, v199
	v_lshlrev_b32_e32 v96, 16, v200
	v_perm_b32 v140, v201, v202, s49
	v_perm_b32 v133, v203, v204, s49
.Lx584_c:
	v_lshlrev_b32_e32 v16, 16, v89
	v_cndmask_b32_e64 v16, 0, v16, s[8:9]
	v_lshlrev_b32_e32 v17, 16, v138
	ds_write_b32 v137, v16 offset:17920
	v_add_f32_e32 v16, 0, v16
	v_cndmask_b32_e64 v17, 0, v17, s[8:9]
	v_add_f32_e32 v16, v17, v16
	ds_write_b32 v139, v17 offset:17920
	ds_write_b32 v163, v16 offset:24064
	s_waitcnt lgkmcnt(0)
	s_barrier
	ds_read2st64_b32 v[184:185], v162 offset0:94 offset1:95
	ds_read2st64_b32 v[186:187], v162 offset0:96 offset1:97
	ds_read2st64_b32 v[188:189], v162 offset0:98 offset1:99
	ds_read_b32 v190, v162 offset:25600
	s_waitcnt lgkmcnt(0)
	s_and_b64 vcc, exec, s[38:39]
	v_add_f32_e32 v16, 0, v184
	v_cndmask_b32_e64 v16, v16, 0, s[4:5]
	v_cndmask_b32_e64 v17, 0, v185, s[10:11]
	v_add_f32_e32 v18, v16, v17
	v_cndmask_b32_e64 v16, 0, v186, s[12:13]
	v_add_f32_e32 v16, v18, v16
	v_cndmask_b32_e64 v17, 0, v187, s[14:15]
	v_add_f32_e32 v18, v16, v17
	v_cndmask_b32_e64 v16, 0, v188, s[16:17]
	v_add_f32_e32 v16, v18, v16
	v_cndmask_b32_e64 v17, 0, v189, s[18:19]
	v_add_f32_e32 v16, v16, v17
	v_cndmask_b32_e64 v17, 0, v190, s[20:21]
	v_add_f32_e32 v16, v16, v17
	v_mov_b32_e32 v17, 0
	s_cbranch_vccnz .LBB0_586
	v_and_b32_e32 v25, 0xffff0000, v133
	v_lshlrev_b32_e32 v24, 16, v133
	v_pk_add_f32 v[28:29], v[96:97], v[24:25] neg_lo:[0,1] neg_hi:[0,1]
	v_mov_b32_e32 v27, v25
	v_fmac_f32_e32 v27, v63, v29
	v_mov_b32_e32 v30, v24
	v_mul_f32_e32 v20, v65, v27
	s_waitcnt vmcnt(13)
	v_fmac_f32_e32 v30, v69, v28
	v_mul_f32_e32 v28, v20, v20
	ds_read_b32 v19, v137 offset:17920
	v_mul_f32_e32 v18, 0xbfb8aa3b, v16
	v_mov_b32_dpp v28, v28 quad_perm:[1,0,3,2] row_mask:0xf bank_mask:0xf bound_ctrl:1
	v_fmac_f32_e32 v28, v20, v20
	v_exp_f32_e32 v18, v18
	s_waitcnt lgkmcnt(0)
	v_add_f32_e32 v16, v16, v19
	v_add_f32_dpp v28, v28, v28 quad_perm:[2,3,0,1] row_mask:0xf bank_mask:0xf bound_ctrl:1
	v_mul_f32_e32 v19, 0xbfb8aa3b, v16
	v_exp_f32_e32 v21, v19
	v_add_f32_dpp v28, v28, v28 row_ror:4 row_mask:0xf bank_mask:0xf bound_ctrl:1
	v_mul_f32_e32 v19, 0x3fb8aa3b, v16
	v_lshlrev_b32_e32 v23, 16, v87
	v_add_f32_dpp v28, v28, v28 row_ror:8 row_mask:0xf bank_mask:0xf bound_ctrl:1
	v_exp_f32_e32 v22, v19
	v_readlane_b32 s3, v28, 16
	v_readlane_b32 s52, v28, 48
	v_readlane_b32 s0, v28, 0
	v_readlane_b32 s1, v28, 32
	v_mov_b32_e32 v28, s3
	v_mov_b32_e32 v29, s52
	v_pk_add_f32 v[28:29], s[0:1], v[28:29]
	v_sub_f32_e32 v19, v142, v23
	v_add_f32_e32 v28, v28, v29
	v_fma_f32 v19, v61, v19, v23
	v_rsq_f32_e32 v28, v28
	v_lshlrev_b32_e32 v26, 16, v134
	v_mov_b32_e32 v142, v23
	v_mov_b64_e32 v[96:97], v[24:25]
	v_min_f32_e32 v28, 0x5368d4a5, v28
	s_nop 0
	v_mul_f32_e32 v28, v20, v28
	v_xor_b32_e32 v20, 0x80000000, v28
	v_pk_mul_f32 v[18:19], v[18:19], v[20:21]
	s_nop 0
	v_cvt_pk_bf16_f32 v18, v18, v19
	v_add_f32_e32 v19, -1.0, v26
	v_fma_f32 v29, v67, v19, 1.0
	v_pk_mul_f32 v[20:21], v[28:29], v[26:27]
	s_nop 0
	v_pk_mul_f32 v[20:21], v[22:23], v[20:21] op_sel_hi:[0,1]
	v_bfe_u32 v22, v30, 16, 1
	v_cvt_pk_bf16_f32 v19, v20, v21
	v_add3_u32 v22, v30, v22, s51
	v_lshrrev_b32_e32 v20, 16, v18
	v_lshrrev_b32_e32 v21, 16, v19
	v_lshrrev_b32_e32 v22, 16, v22
	s_branch .LBB0_587

.LBB0_587:
	s_and_b64 vcc, exec, s[38:39]
	ds_write_b16 v167, v18
	ds_write_b16 v167, v20 offset:2304
	ds_write_b16 v167, v19 offset:4608
	ds_write_b16 v167, v21 offset:6912
	ds_write_b16 v167, v22 offset:9216
	s_cbranch_vccnz .LBB0_589
	v_mul_f32_e32 v17, 0xbfb8aa3b, v16
	v_exp_f32_e32 v18, v17
	ds_read_b32 v17, v139 offset:17920
	v_and_b32_e32 v25, 0xffff0000, v140
	v_lshlrev_b32_e32 v24, 16, v140
	v_lshlrev_b32_e32 v23, 16, v46
	v_pk_add_f32 v[28:29], v[96:97], v[24:25] neg_lo:[0,1] neg_hi:[0,1]
	s_waitcnt lgkmcnt(0)
	v_add_f32_e32 v16, v16, v17
	v_mul_f32_e32 v17, 0xbfb8aa3b, v16
	v_exp_f32_e32 v21, v17
	v_mul_f32_e32 v17, 0x3fb8aa3b, v16
	v_mov_b32_e32 v27, v25
	v_exp_f32_e32 v22, v17
	v_sub_f32_e32 v17, v142, v23
	v_fmac_f32_e32 v27, v63, v29
	v_fma_f32 v19, v61, v17, v23
	v_mul_f32_e32 v17, v65, v27
	v_mul_f32_e32 v20, v17, v17
	v_mov_b32_e32 v30, v24
	s_waitcnt vmcnt(13)
	v_fmac_f32_e32 v30, v69, v28
	v_mov_b32_dpp v20, v20 quad_perm:[1,0,3,2] row_mask:0xf bank_mask:0xf bound_ctrl:1
	v_fmac_f32_e32 v20, v17, v17
	v_lshlrev_b32_e32 v26, 16, v141
	v_mov_b32_e32 v142, v23
	v_add_f32_dpp v20, v20, v20 quad_perm:[2,3,0,1] row_mask:0xf bank_mask:0xf bound_ctrl:1
	v_mov_b64_e32 v[96:97], v[24:25]
	s_nop 0
	v_add_f32_dpp v20, v20, v20 row_ror:4 row_mask:0xf bank_mask:0xf bound_ctrl:1
	s_nop 1
	v_add_f32_dpp v20, v20, v20 row_ror:8 row_mask:0xf bank_mask:0xf bound_ctrl:1
	s_nop 0
	v_readlane_b32 s3, v20, 16
	v_readlane_b32 s52, v20, 48
	v_readlane_b32 s0, v20, 0
	v_readlane_b32 s1, v20, 32
	v_mov_b32_e32 v28, s3
	v_mov_b32_e32 v29, s52
	v_pk_add_f32 v[28:29], s[0:1], v[28:29]
	s_nop 0
	v_add_f32_e32 v20, v28, v29
	v_rsq_f32_e32 v20, v20
	s_nop 0
	v_min_f32_e32 v20, 0x5368d4a5, v20
	s_nop 0
	v_mul_f32_e32 v28, v17, v20
	v_xor_b32_e32 v20, 0x80000000, v28
	v_pk_mul_f32 v[18:19], v[18:19], v[20:21]
	v_bfe_u32 v21, v30, 16, 1
	v_cvt_pk_bf16_f32 v17, v18, v19
	v_add_f32_e32 v18, -1.0, v26
	v_fma_f32 v29, v67, v18, 1.0
	v_pk_mul_f32 v[18:19], v[28:29], v[26:27]
	v_add3_u32 v21, v30, v21, s51
	v_pk_mul_f32 v[18:19], v[22:23], v[18:19] op_sel_hi:[0,1]
	v_cvt_pk_bf16_f32 v18, v18, v19
	v_lshrrev_b32_e32 v19, 16, v17
	v_lshrrev_b32_e32 v20, 16, v18
	v_lshrrev_b32_e32 v21, 16, v21
	s_branch .LBB0_590

.LBB0_613:
	s_waitcnt vmcnt(13)
	v_lshlrev_b32_e32 v135, 16, v195
	v_lshlrev_b32_e32 v95, 16, v196
	v_lshlrev_b32_e32 v94, 16, v197
	v_perm_b32 v77, v191, v192, s49
	v_perm_b32 v83, v193, v194, s49
	v_lshlrev_b32_e32 v16, 16, v75
	v_cndmask_b32_e64 v16, 0, v16, s[8:9]
	v_lshlrev_b32_e32 v17, 16, v81
	ds_write_b32 v137, v16 offset:13824
	v_add_f32_e32 v16, 0, v16
	v_cndmask_b32_e64 v17, 0, v17, s[8:9]
	v_add_f32_e32 v16, v17, v16
	s_add_i32 s72, s72, 32
	s_add_i32 s2, s2, 2
	s_mov_b64 s[0:1], 0
	ds_write_b32 v139, v17 offset:13824
	ds_write_b32 v163, v16 offset:22016
	s_branch .LBB0_555
